# attention: V tile stored in natural key order in LDS so packed P needs no lane re-ordering; 8 v_permlane32_swap per P tile removed
# speedup vs baseline: 1.0061x; 1.0061x over previous
; #define VMW() asm volatile("s_waitcnt vmcnt(0)" ::: "memory")
; #define SLOAD_H(Kp, Vp, k0) do { S.st_v0 = load8(ROW(Vp, k0, sr)); S.st_v1 = load8(ROW(Vp, k0, 32 + sr));              \
;                          S.st_k0 = load8(ROW(Kp, k0, sr)); S.st_k1 = load8(ROW(Kp, k0, 32 + sr)); } while (0)
; #define SWRITE_HK(bf) do { *(bf16x8*)(K_lds + (bf) * SHM_K + kws) = S.st_k0; *(bf16x8*)(K_lds + (bf) * SHM_K + kws + 32 * 256) = S.st_k1; } while (0)
; __device__ __forceinline__ void attn_prime(const BlockRef& cur, char* lds, Seam& S) {
;     const int tid = threadIdx.x, wid = __builtin_amdgcn_readfirstlane(tid >> 6), lane = tid & 63, r32 = lane & 31, hi = lane >> 5;
;     const int sr = tid >> 4, sc = (tid & 15) * 8, kws = KSWZ(sr, sc * 2); char* K_lds = lds + 2 * SHM_V;
; #pragma unroll
;     for (int d0 = 0; d0 < 8; ++d0) S.qr[d0] = load8(cur.Q + (size_t)(wid * QBLK + r32) * LD + d0 * 16 + hi * 8);
;     SLOAD_H(cur.K, cur.V, 0); VMW(); SWRITE_HK(0);
;     __syncthreads();
; __device__ __forceinline__ void attn_phase(char* lds, const bf16* Q, const bf16* K, const bf16* V, bf16* O, const unsigned long long* MW, int first, int stride) {
;     constexpr int total = (DUP_PHASE == 5) ? 1024 : 512;
;     int L = first; if (L >= total) return;
;     Item it = decode(L); int pass = 0;
;     BlockRef cur = mkref(it, 0, Q, K, V, O, MW);
.LBB0_1289:
	s_cmp_lt_i32 s54, 6
	s_cselect_b64 s[8:9], -1, 0
	s_and_b64 s[0:1], s[8:9], s[0:1]
	s_andn2_b64 vcc, exec, s[0:1]
	s_cbranch_vccnz .LBB0_1447
	s_cmpk_gt_i32 s2, 0x1ff
	s_cbranch_scc1 .LBB0_1447
	s_add_u32 s3, s52, 0xc000000
	s_addc_u32 s15, s53, 0
	s_add_u32 s33, s52, 0x10000000
	s_addc_u32 s35, s53, 0
	s_add_u32 s56, s52, 0x14000000
	s_addc_u32 s57, s53, 0
	s_add_u32 s58, s52, 0x2e00000
	s_addc_u32 s59, s53, 0
	s_lshl_b32 s4, s2, 3
	s_bfe_u32 s1, s2, 0x30003
	s_and_b32 s4, s4, 56
	s_lshl_b32 s5, s4, 9
	s_lshl_b32 s38, s1, 8
	s_bfe_u32 s0, s2, 0x30006
	s_xor_b32 s73, s1, 15
	s_or_b32 s1, s5, s38
	s_or_b32 s72, s4, s0
	s_lshl_b32 s5, s1, 11
	s_add_u32 s6, s3, s5
	s_addc_u32 s7, s15, 0
	s_lshl_b32 s0, s0, 8
	s_add_u32 s10, s6, s0
	s_addc_u32 s11, s7, 0
	s_add_u32 s5, s30, s5
	s_addc_u32 s6, s31, 0
	s_add_u32 s66, s5, s0
	s_addc_u32 s67, s6, 0
	s_lshl_b32 s4, s4, 20
	s_add_u32 s5, s33, s4
	s_addc_u32 s7, s35, 0
	s_add_u32 s6, s5, s0
	s_addc_u32 s7, s7, 0
	s_add_u32 s4, s56, s4
	s_addc_u32 s5, s57, 0
	s_add_u32 s70, s4, s0
	s_addc_u32 s71, s5, 0
	s_lshl_b32 s0, s1, 9
	s_add_u32 s68, s58, s0
	v_readfirstlane_b32 s0, v0
	s_addc_u32 s69, s59, 0
	s_lshr_b32 s0, s0, 1
	s_waitcnt vmcnt(0)
	v_and_b32_e32 v30, 31, v0
	s_and_b32 s0, s0, 0x7fffffe0
	v_or_b32_e32 v166, s0, v30
	v_mov_b32_e32 v167, 0
	v_lshlrev_b64 v[2:3], 11, v[166:167]
	v_lshrrev_b32_e32 v1, 1, v0
	v_lshl_add_u64 v[2:3], s[10:11], 0, v[2:3]
	v_and_b32_e32 v166, 16, v1
	v_lshrrev_b32_e32 v1, 4, v0
	v_lshlrev_b32_e32 v13, 3, v0
	v_lshl_add_u64 v[10:11], v[2:3], 0, v[166:167]
	v_and_b32_e32 v12, 0x78, v13
	v_lshlrev_b32_e32 v166, 11, v1
	v_lshlrev_b32_e32 v14, 1, v12
	v_mov_b32_e32 v15, v167
	v_lshl_add_u64 v[2:3], s[6:7], 0, v[166:167]
	s_mov_b32 s0, 0x10000
	v_lshl_add_u64 v[16:17], v[2:3], 0, v[14:15]
	v_add_co_u32_e32 v18, vcc, s0, v16
	v_bfe_u32 v21, v0, 4, 2
	s_nop 0
	v_addc_co_u32_e32 v19, vcc, 0, v17, vcc
	global_load_dwordx4 v[2:5], v[16:17], off
	global_load_dwordx4 v[6:9], v[18:19], off
	global_load_dwordx4 v[126:129], v[10:11], off
	global_load_dwordx4 v[122:125], v[10:11], off offset:32
	global_load_dwordx4 v[118:121], v[10:11], off offset:64
	global_load_dwordx4 v[114:117], v[10:11], off offset:96
	global_load_dwordx4 v[110:113], v[10:11], off offset:128
	global_load_dwordx4 v[106:109], v[10:11], off offset:160
	global_load_dwordx4 v[102:105], v[10:11], off offset:192
	global_load_dwordx4 v[98:101], v[10:11], off offset:224
	v_lshl_add_u64 v[10:11], s[70:71], 0, v[166:167]
	v_lshrrev_b32_e32 v18, 3, v0
	v_lshl_add_u64 v[10:11], v[10:11], 0, v[14:15]
	v_lshrrev_b32_e32 v19, 5, v0
	v_and_b32_e32 v25, 8, v1
	v_add_co_u32_e32 v18, vcc, s0, v10
	v_and_or_b32 v21, v1, 4, v21
	s_nop 0
	v_addc_co_u32_e32 v19, vcc, 0, v11, vcc
	global_load_dwordx4 v[130:133], v[10:11], off
	global_load_dwordx4 v[134:137], v[18:19], off
	s_movk_i32 s1, 0x70
	v_lshlrev_b32_e32 v24, 8, v1
	v_lshlrev_b32_e32 v16, 10, v1
	v_or_b32_e32 v27, 32, v1
	v_and_or_b32 v1, v1, 16, v25
	v_bitop3_b32 v15, v14, v0, s1 bitop3:0x78
	v_lshrrev_b32_e32 v20, 5, v162
	v_bfe_u32 v26, v13, 5, 2
	v_lshrrev_b32_e32 v1, 1, v1
	v_add3_u32 v15, 0, v24, v15
	v_lshlrev_b32_e32 v22, 4, v0
	v_and_or_b32 v11, v27, 48, v25
	v_or_b32_e32 v1, v1, v26
	s_waitcnt vmcnt(0)
	v_and_b32_e32 v17, 0x70, v0
	v_lshlrev_b32_e32 v10, 6, v21
	v_and_b32_e32 v18, 48, v14
	v_lshrrev_b32_e32 v11, 1, v11
	v_lshlrev_b32_e32 v1, 9, v1
	v_lshlrev_b32_e32 v23, 1, v0
	v_bitop3_b32 v14, v14, v24, v17 bitop3:0xde
	v_or_b32_e32 v11, v11, v26
	v_or3_b32 v17, v1, v10, v18
	v_and_b32_e32 v1, 0x118, v13
	v_and_b32_e32 v13, 1, v0
	v_and_b32_e32 v28, 0xc0, v22
	v_and_b32_e32 v23, 32, v23
	v_lshlrev_b32_e32 v11, 9, v11
	s_cmp_lg_u32 0, -1
	v_cmp_eq_u32_e64 s[4:5], 0, v13
	v_and_b32_e32 v13, 15, v0
	v_or3_b32 v10, v11, v10, v18
	v_or3_b32 v1, v23, v28, v1
	s_cselect_b32 s0, 0, 0
	v_lshlrev_b32_e32 v170, 4, v13
	v_lshlrev_b32_e32 v13, 7, v0
	s_mov_b32 s13, 0
	v_add_u32_e32 v1, s0, v1
	v_lshlrev_b32_e32 v163, 2, v20
	v_cmp_gt_u32_e64 s[0:1], 32, v162
	v_lshlrev_b32_e32 v168, 13, v20
	s_waitcnt vmcnt(11)
	ds_write_b128 v15, v[2:5] offset:32768
	s_waitcnt vmcnt(10)
	ds_write_b128 v15, v[6:9] offset:40960
	v_lshlrev_b32_e32 v2, 4, v20
	v_and_b32_e32 v4, 0x70, v22
	v_or_b32_e32 v6, 32, v2
	v_xad_u32 v7, v6, v4, 0
	v_or_b32_e32 v6, 64, v2
	v_xad_u32 v5, v2, v4, 0
	v_xad_u32 v9, v6, v4, 0
	v_or_b32_e32 v2, 0x60, v2
	v_lshlrev_b32_e32 v6, 10, v27
	v_lshlrev_b32_e32 v3, 8, v30
	v_xad_u32 v11, v2, v4, 0
	v_or_b32_e32 v2, 0x10000, v16
	v_or_b32_e32 v4, 0x18000, v16
	v_lshlrev_b32_e32 v8, 3, v20
	v_lshlrev_b32_e32 v178, 1, v6
	v_mbcnt_lo_u32_b32 v6, -1, 0
	v_mov_b32_e32 v169, v167
	v_lshl_or_b32 v254, v30, 9, 16
	v_mov_b32_e32 v171, v167
	v_and_b32_e32 v252, 0xf800, v13
	v_mov_b32_e32 v253, v167
	s_mov_b32 s74, 0xff800000
	s_mov_b32 s75, 0x41000000
	s_mov_b32 s14, 0x3e0293ee
	s_mov_b32 s76, 0x40000
	s_mov_b32 s77, 0x50000
	v_lshlrev_b32_e32 v164, 1, v16
	v_lshlrev_b32_e32 v176, 1, v12
	v_lshlrev_b32_e32 v180, 1, v8
	v_mbcnt_hi_u32_b32 v196, -1, v6
	v_lshlrev_b32_e32 v166, 1, v30
	v_add_u32_e32 v197, 0, v17
	v_add_u32_e32 v198, 0, v10
	v_lshlrev_b32_e32 v182, 1, v2
	v_lshlrev_b32_e32 v184, 1, v4
	v_add_u32_e32 v199, v5, v3
	v_add_u32_e32 v200, v7, v3
	v_add_u32_e32 v201, v9, v3
	v_add_u32_e32 v202, v11, v3
	v_mov_b32_e32 v203, 0xf149f2ca
	v_add_u32_e32 v204, 0, v14
	s_mov_b32 s79, 0
	s_mov_b32 s78, s2
	s_waitcnt lgkmcnt(0)
	s_barrier
	s_branch .LBB0_1293

; __device__ __forceinline__ void finishSM(f32x16& p0, f32x16& p1, float alpha, float& l_reg, bf16x8& pa0, bf16x8& pa1, bf16x8& pa2, bf16x8& pa3) {
;     ...
;     PK4(p0, 0, pa0); PK4(p0, 8, pa1); PK4(p1, 0, pa2); PK4(p1, 8, pa3);
.LBB0_1299:
	global_load_dwordx2 v[146:147], v179, s[68:69] offset:-8
	s_add_u32 s98, s16, 0x40000
	s_addc_u32 s99, s17, 0
	global_load_dwordx4 v[130:133], v188, s[98:99]
	s_add_u32 s98, s16, 0x50000
	s_addc_u32 s99, s17, 0
	global_load_dwordx4 v[134:137], v188, s[98:99]
	s_add_u32 s98, s100, 0x40000
	s_addc_u32 s99, s101, 0
	global_load_dwordx4 v[138:141], v188, s[98:99]
	s_add_u32 s98, s100, 0x50000
	s_addc_u32 s99, s101, 0
	global_load_dwordx4 v[142:145], v188, s[98:99]
	ds_read_b128 v[66:69], v199 offset:49152
	ds_read_b128 v[82:85], v199 offset:57344
	ds_read_b128 v[172:175], v200 offset:49152
	ds_read_b128 v[232:235], v200 offset:57344
	ds_read_b128 v[236:239], v201 offset:49152
	ds_read_b128 v[240:243], v201 offset:57344
	ds_read_b128 v[244:247], v202 offset:49152
	v_exp_f32_e32 v209, v150
	v_add_f32_e32 v150, v220, v219
	v_add_f32_e32 v150, v221, v150
	s_waitcnt lgkmcnt(6)
	v_mfma_f32_32x32x16_bf16 v[66:81], v[66:69], v[126:129], 0
	v_add_f32_e32 v150, v222, v150
	v_add_f32_e32 v150, v223, v150
	v_add_f32_e32 v150, v225, v150
	v_add_f32_e32 v150, v224, v150
	v_add_f32_e32 v150, v226, v150
	s_waitcnt lgkmcnt(5)
	v_mfma_f32_32x32x16_bf16 v[82:97], v[82:85], v[126:129], 0
	v_add_f32_e32 v150, v211, v150
	v_add_f32_e32 v150, v212, v150
	v_exp_f32_e32 v194, v194
	s_waitcnt lgkmcnt(4)
	v_mfma_f32_32x32x16_bf16 v[66:81], v[172:175], v[122:125], v[66:81]
	ds_read_b128 v[172:175], v202 offset:57344
	v_exp_f32_e32 v195, v195
	v_exp_f32_e32 v192, v192
	v_exp_f32_e32 v193, v193
	s_waitcnt lgkmcnt(4)
	v_mfma_f32_32x32x16_bf16 v[82:97], v[232:235], v[122:125], v[82:97]
	ds_read_b128 v[232:235], v199 offset:49280
	v_exp_f32_e32 v158, v158
	v_exp_f32_e32 v159, v159
	s_waitcnt lgkmcnt(4)
	v_mfma_f32_32x32x16_bf16 v[66:81], v[236:239], v[118:121], v[66:81]
	ds_read_b128 v[236:239], v199 offset:57472
	v_exp_f32_e32 v207, v154
	v_exp_f32_e32 v208, v155
	v_exp_f32_e32 v210, v151
	s_waitcnt lgkmcnt(4)
	v_mfma_f32_32x32x16_bf16 v[82:97], v[240:243], v[118:121], v[82:97]
	ds_read_b128 v[240:243], v200 offset:49280
	v_exp_f32_e32 v160, v160
	v_exp_f32_e32 v161, v161
	s_waitcnt lgkmcnt(4)
	v_mfma_f32_32x32x16_bf16 v[66:81], v[244:247], v[114:117], v[66:81]
	ds_read_b128 v[244:247], v200 offset:57472
	v_exp_f32_e32 v227, v156
	v_cvt_pk_bf16_f32 v151, v224, v226
	v_cvt_pk_bf16_f32 v154, v214, v216
	v_cvt_pk_bf16_f32 v155, v217, v218
	v_cvt_pk_bf16_f32 v156, v194, v195
	s_waitcnt lgkmcnt(4)
	v_mfma_f32_32x32x16_bf16 v[82:97], v[172:175], v[114:117], v[82:97]
	ds_read_b128 v[172:175], v201 offset:49280
	v_exp_f32_e32 v228, v157
	v_exp_f32_e32 v229, v152
	s_waitcnt lgkmcnt(4)
	v_mfma_f32_32x32x16_bf16 v[66:81], v[232:235], v[110:113], v[66:81]
	ds_read_b128 v[232:235], v201 offset:57472
	v_exp_f32_e32 v230, v153
	v_cvt_pk_bf16_f32 v152, v211, v212
	v_cvt_pk_bf16_f32 v153, v213, v215
	v_cvt_pk_bf16_f32 v157, v192, v193
	v_cvt_pk_bf16_f32 v211, v229, v230
	s_waitcnt lgkmcnt(4)
	v_mfma_f32_32x32x16_bf16 v[82:97], v[236:239], v[110:113], v[82:97]
	ds_read_b128 v[236:239], v202 offset:49280
	v_add_f32_e32 v249, v213, v150
	v_add_f32_e32 v249, v215, v249
	v_add_f32_e32 v249, v214, v249
	s_waitcnt lgkmcnt(4)
	v_mfma_f32_32x32x16_bf16 v[66:81], v[240:243], v[106:109], v[66:81]
	ds_read_b128 v[240:243], v202 offset:57472
	v_add_f32_e32 v249, v216, v249
	v_add_f32_e32 v249, v217, v249
	v_add_f32_e32 v249, v218, v249
	v_add_f32_e32 v249, v194, v249
	v_add_f32_e32 v248, v195, v249
	s_waitcnt lgkmcnt(4)
	v_mfma_f32_32x32x16_bf16 v[82:97], v[244:247], v[106:109], v[82:97]
	v_add_f32_e32 v248, v192, v248
	v_add_f32_e32 v248, v193, v248
	v_add_f32_e32 v248, v158, v248
	v_add_f32_e32 v248, v159, v248
	v_add_f32_e32 v248, v207, v248
	s_waitcnt lgkmcnt(3)
	v_mfma_f32_32x32x16_bf16 v[66:81], v[172:175], v[102:105], v[66:81]
	v_add_f32_e32 v248, v208, v248
	v_add_f32_e32 v248, v209, v248
	v_add_f32_e32 v248, v210, v248
	v_add_f32_e32 v248, v160, v248
	v_add_f32_e32 v248, v161, v248
	s_waitcnt lgkmcnt(2)
	v_mfma_f32_32x32x16_bf16 v[82:97], v[232:235], v[102:105], v[82:97]
	v_add_f32_e32 v248, v227, v248
	v_add_f32_e32 v248, v228, v248
	v_add_f32_e32 v248, v229, v248
	v_add_f32_e32 v181, v230, v248
	s_waitcnt lgkmcnt(1)
	v_mfma_f32_32x32x16_bf16 v[66:81], v[236:239], v[98:101], v[66:81]
	v_cvt_pk_bf16_f32 v148, v219, v220
	v_cvt_pk_bf16_f32 v149, v221, v222
	v_cvt_pk_bf16_f32 v150, v223, v225
	v_cvt_pk_bf16_f32 v158, v158, v159
	v_cvt_pk_bf16_f32 v159, v207, v208
	s_waitcnt lgkmcnt(0)
	v_mfma_f32_32x32x16_bf16 v[82:97], v[240:243], v[98:101], v[82:97]
	v_cvt_pk_bf16_f32 v208, v209, v210
	v_cvt_pk_bf16_f32 v210, v227, v228
	v_cvt_pk_bf16_f32 v209, v160, v161
	ds_read_b64_tr_b16 v[172:173], v1 offset:0x0
	ds_read_b64_tr_b16 v[174:175], v1 offset:0x800
	ds_read_b64_tr_b16 v[212:213], v1 offset:0x200
	ds_read_b64_tr_b16 v[214:215], v1 offset:0xa00
	ds_read_b64_tr_b16 v[216:217], v1 offset:0x400
	ds_read_b64_tr_b16 v[218:219], v1 offset:0xc00
	ds_read_b64_tr_b16 v[220:221], v1 offset:0x600
	ds_read_b64_tr_b16 v[222:223], v1 offset:0xe00
	ds_read_b64_tr_b16 v[224:225], v1 offset:0x1000
	ds_read_b64_tr_b16 v[226:227], v1 offset:0x1800
	ds_read_b64_tr_b16 v[232:233], v1 offset:0x1200
	ds_read_b64_tr_b16 v[234:235], v1 offset:0x1a00
	ds_read_b64_tr_b16 v[236:237], v1 offset:0x1400
	ds_read_b64_tr_b16 v[238:239], v1 offset:0x1c00
	s_nop 0
	s_waitcnt lgkmcnt(12)
	v_mfma_f32_32x32x16_bf16 v[2:17], v[148:151], v[172:175], v[2:17]
	ds_read_b64_tr_b16 v[240:241], v1 offset:0x1600
	ds_read_b64_tr_b16 v[242:243], v1 offset:0x1e00
	s_waitcnt vmcnt(4)
	v_lshrrev_b32_e32 v160, v163, v146
	v_lshrrev_b32_e32 v161, v163, v147
	v_bfe_i32 v146, v160, 0, 1
	v_bfe_i32 v147, v161, 0, 1
	v_bitop3_b32 v146, v66, s74, v146 bitop3:0xe4
	v_bitop3_b32 v66, v82, s74, v147 bitop3:0xe4
	s_waitcnt lgkmcnt(12)
; __device__ __forceinline__ void sel_mask_tile(f32x16& p0, f32x16& p1, unsigned wlo, unsigned whi, int hi) {
;     const unsigned NEGB = 0xff800000u;
;     const unsigned lo = wlo >> (4 * hi), h2 = whi >> (4 * hi);
; #pragma unroll
;     for (int r = 0; r < 16; ++r) {
;         const int c = (r & 3) + 8 * (r >> 2);
;         const unsigned m0 = (unsigned)__builtin_amdgcn_sbfe((int)lo, c, 1), m1 = (unsigned)__builtin_amdgcn_sbfe((int)h2, c, 1);
;         p0[r] = __uint_as_float((__float_as_uint(p0[r]) & m0) | (NEGB & ~m0));
;         p1[r] = __uint_as_float((__float_as_uint(p1[r]) & m1) | (NEGB & ~m1));
;     }
; }
; __device__ __forceinline__ void partialSM(f32x16& p0, f32x16& p1, float& m_reg, float& mn, float& alpha) {
;     float pmax = p0[0];
; #pragma unroll
;     for (int r = 1; r < 16; ++r) pmax = fmaxf(pmax, p0[r]);
; #pragma unroll
;     for (int r = 0; r < 16; ++r) pmax = fmaxf(pmax, p1[r]);
;     { auto rr = __builtin_amdgcn_permlane32_swap(__float_as_uint(pmax), __float_as_uint(pmax), false, false);
;       pmax = fmaxf(__uint_as_float(rr[0]), __uint_as_float(rr[1])); }
; template <int VB>
; __device__ __forceinline__ void pv_tile(f32x16* o, int vb0, bf16x8 pa0, bf16x8 pa1, bf16x8 pa2, bf16x8 pa3) {
;     ...
;     PV_D0(0); PV_D0(1); PV_D0(2); PV_D0(3);
	v_mfma_f32_32x32x16_bf16 v[50:65], v[148:151], v[212:215], v[50:65]
	ds_read_b64_tr_b16 v[244:245], v1 offset:0x2000
	ds_read_b64_tr_b16 v[246:247], v1 offset:0x2800
	v_bfe_i32 v82, v160, 1, 1
	v_bfe_i32 v147, v161, 1, 1
	v_bitop3_b32 v82, v67, s74, v82 bitop3:0xe4
	v_bitop3_b32 v67, v83, s74, v147 bitop3:0xe4
	v_bfe_i32 v83, v160, 2, 1
	v_bfe_i32 v147, v161, 2, 1
	s_waitcnt lgkmcnt(12)
	v_mfma_f32_32x32x16_bf16 v[34:49], v[148:151], v[216:219], v[34:49]
	ds_read_b64_tr_b16 v[248:249], v1 offset:0x2200
	ds_read_b64_tr_b16 v[250:251], v1 offset:0x2a00
	v_bitop3_b32 v83, v68, s74, v83 bitop3:0xe4
	v_bitop3_b32 v68, v84, s74, v147 bitop3:0xe4
	v_bfe_i32 v84, v160, 3, 1
	s_waitcnt lgkmcnt(12)
	v_mfma_f32_32x32x16_bf16 v[18:33], v[148:151], v[220:223], v[18:33]
	ds_read_b64_tr_b16 v[220:221], v1 offset:0x2400
	ds_read_b64_tr_b16 v[222:223], v1 offset:0x2c00
	v_bfe_i32 v148, v161, 3, 1
	v_bitop3_b32 v147, v69, s74, v84 bitop3:0xe4
	v_bfe_i32 v84, v160, 8, 1
	v_bitop3_b32 v69, v85, s74, v148 bitop3:0xe4
	v_bfe_i32 v85, v161, 8, 1
	v_bitop3_b32 v148, v70, s74, v84 bitop3:0xe4
	v_bfe_i32 v84, v160, 9, 1
	s_waitcnt lgkmcnt(12)
	v_mfma_f32_32x32x16_bf16 v[2:17], v[152:155], v[224:227], v[2:17]
	ds_read_b64_tr_b16 v[224:225], v1 offset:0x2600
	ds_read_b64_tr_b16 v[226:227], v1 offset:0x2e00
	v_bitop3_b32 v70, v86, s74, v85 bitop3:0xe4
	v_bfe_i32 v85, v161, 9, 1
	v_bitop3_b32 v149, v71, s74, v84 bitop3:0xe4
	v_bfe_i32 v84, v160, 10, 1
	v_bitop3_b32 v71, v87, s74, v85 bitop3:0xe4
	v_bfe_i32 v85, v161, 10, 1
	s_waitcnt lgkmcnt(12)
	v_mfma_f32_32x32x16_bf16 v[50:65], v[152:155], v[232:235], v[50:65]
	ds_read_b64_tr_b16 v[232:233], v1 offset:0x3000
	ds_read_b64_tr_b16 v[234:235], v1 offset:0x3800
	v_bitop3_b32 v87, v72, s74, v84 bitop3:0xe4
	v_bfe_i32 v84, v160, 11, 1
	v_bitop3_b32 v72, v88, s74, v85 bitop3:0xe4
	v_bfe_i32 v85, v161, 11, 1
	v_bitop3_b32 v88, v73, s74, v84 bitop3:0xe4
	v_bfe_i32 v73, v160, 16, 1
	v_bitop3_b32 v84, v89, s74, v85 bitop3:0xe4
	s_waitcnt lgkmcnt(12)
	v_mfma_f32_32x32x16_bf16 v[34:49], v[152:155], v[236:239], v[34:49]
	ds_read_b64_tr_b16 v[236:237], v1 offset:0x3200
	ds_read_b64_tr_b16 v[238:239], v1 offset:0x3a00
	v_bfe_i32 v85, v161, 16, 1
	v_bitop3_b32 v89, v74, s74, v73 bitop3:0xe4
	v_bfe_i32 v73, v160, 17, 1
	v_bfe_i32 v74, v161, 17, 1
	v_bitop3_b32 v85, v90, s74, v85 bitop3:0xe4
	v_bitop3_b32 v90, v75, s74, v73 bitop3:0xe4
	s_waitcnt lgkmcnt(12)
	v_mfma_f32_32x32x16_bf16 v[18:33], v[152:155], v[240:243], v[18:33]
	ds_read_b64_tr_b16 v[240:241], v1 offset:0x3400
	ds_read_b64_tr_b16 v[242:243], v1 offset:0x3c00
	v_bitop3_b32 v86, v91, s74, v74 bitop3:0xe4
	v_bfe_i32 v73, v160, 18, 1
	v_bfe_i32 v74, v161, 18, 1
	v_bitop3_b32 v91, v76, s74, v73 bitop3:0xe4
	v_bitop3_b32 v76, v92, s74, v74 bitop3:0xe4
	v_bfe_i32 v73, v160, 19, 1
	v_bfe_i32 v74, v161, 19, 1
	s_waitcnt lgkmcnt(12)
	v_mfma_f32_32x32x16_bf16 v[2:17], v[156:159], v[244:247], v[2:17]
	ds_read_b64_tr_b16 v[244:245], v1 offset:0x3600
	ds_read_b64_tr_b16 v[246:247], v1 offset:0x3e00
	v_bitop3_b32 v92, v77, s74, v73 bitop3:0xe4
	v_bitop3_b32 v77, v93, s74, v74 bitop3:0xe4
	v_bfe_i32 v73, v160, 24, 1
	v_bfe_i32 v74, v161, 24, 1
	v_bitop3_b32 v93, v78, s74, v73 bitop3:0xe4
	v_bitop3_b32 v78, v94, s74, v74 bitop3:0xe4
	s_waitcnt lgkmcnt(12)
	v_mfma_f32_32x32x16_bf16 v[50:65], v[156:159], v[248:251], v[50:65]
	v_bfe_i32 v73, v160, 25, 1
	v_bfe_i32 v74, v161, 25, 1
	v_bitop3_b32 v79, v79, s74, v73 bitop3:0xe4
	v_bitop3_b32 v73, v95, s74, v74 bitop3:0xe4
	v_bfe_i32 v74, v160, 26, 1
	v_bfe_i32 v75, v161, 26, 1
	v_bitop3_b32 v80, v80, s74, v74 bitop3:0xe4
	s_waitcnt lgkmcnt(10)
	v_mfma_f32_32x32x16_bf16 v[34:49], v[156:159], v[220:223], v[34:49]
	v_bitop3_b32 v74, v96, s74, v75 bitop3:0xe4
	v_bfe_i32 v75, v160, 27, 1
	v_bfe_i32 v94, v161, 27, 1
	v_bitop3_b32 v81, v81, s74, v75 bitop3:0xe4
	v_bitop3_b32 v75, v97, s74, v94 bitop3:0xe4
	s_waitcnt lgkmcnt(8)
	v_mfma_f32_32x32x16_bf16 v[18:33], v[156:159], v[224:227], v[18:33]
	v_max_f32_e32 v94, v146, v82
	v_max3_f32 v94, v94, v83, v147
	v_max3_f32 v94, v94, v148, v149
	v_max3_f32 v94, v94, v87, v88
	v_max3_f32 v94, v94, v89, v90
	v_max3_f32 v94, v94, v91, v92
	s_waitcnt lgkmcnt(6)
	v_mfma_f32_32x32x16_bf16 v[2:17], v[208:211], v[232:235], v[2:17]
	v_max3_f32 v94, v94, v93, v79
	v_max3_f32 v94, v94, v80, v81
	v_max3_f32 v94, v94, v66, v67
	v_max3_f32 v94, v94, v68, v69
	v_max3_f32 v94, v94, v70, v71
	v_max3_f32 v94, v94, v72, v84
	s_waitcnt lgkmcnt(4)
	v_mfma_f32_32x32x16_bf16 v[50:65], v[208:211], v[236:239], v[50:65]
	v_max3_f32 v94, v94, v85, v86
	v_max3_f32 v94, v94, v76, v77
	v_max3_f32 v94, v94, v78, v73
	v_max3_f32 v94, v94, v74, v75
	v_mov_b32_e32 v95, v94
	s_nop 1
	v_permlane32_swap_b32_e32 v94, v95
	s_waitcnt lgkmcnt(2)
	v_mfma_f32_32x32x16_bf16 v[34:49], v[208:211], v[240:243], v[34:49]
	v_max_f32_e32 v94, v94, v95
	v_sub_f32_e32 v95, v94, v206
	v_max_f32_e32 v94, v206, v94
	v_sub_f32_e32 v96, v206, v94
	s_waitcnt lgkmcnt(0)
	v_mfma_f32_32x32x16_bf16 v[18:33], v[208:211], v[244:247], v[18:33]
	s_waitcnt vmcnt(0)
	ds_write_b128 v204, v[138:141] offset:32768
	ds_write_b128 v204, v[142:145] offset:40960
	v_mul_f32_e32 v96, 0x3e0293ee, v96
	v_mul_f32_e32 v95, 0x3db504f3, v95
	v_exp_f32_e32 v96, v96
	v_cmp_ge_f32_e32 vcc, s75, v95
	s_cmp_eq_u64 vcc, exec
	s_cselect_b64 s[6:7], -1, 0
	s_barrier
	s_waitcnt vmcnt(0)
	v_cndmask_b32_e64 v208, v96, 1.0, s[6:7]
	v_cmp_gt_f32_e32 vcc, 1.0, v208
	ds_write_b128 v197, v[130:133]
	ds_write_b128 v198, v[134:137]
	s_cbranch_vccz .LBB0_1303
	s_and_saveexec_b64 s[36:37], s[0:1]
	ds_write_b32 v185, v208 offset:128
	s_or_b64 exec, exec, s[36:37]
	s_waitcnt lgkmcnt(0)
	ds_read_b128 v[150:153], v183 offset:224
	ds_read_b128 v[154:157], v183 offset:192
	ds_read_b128 v[158:161], v183 offset:160
	ds_read_b128 v[172:175], v183 offset:128
	s_waitcnt lgkmcnt(3)
	v_pk_mul_f32 v[16:17], v[16:17], v[152:153]
	s_waitcnt lgkmcnt(2)
	v_pk_mul_f32 v[12:13], v[12:13], v[156:157]
	s_waitcnt lgkmcnt(1)
	v_pk_mul_f32 v[8:9], v[8:9], v[160:161]
	s_waitcnt lgkmcnt(0)
	v_pk_mul_f32 v[4:5], v[4:5], v[174:175]
	v_pk_mul_f32 v[14:15], v[14:15], v[150:151]
	v_pk_mul_f32 v[10:11], v[10:11], v[154:155]
	v_pk_mul_f32 v[6:7], v[6:7], v[158:159]
	v_pk_mul_f32 v[2:3], v[2:3], v[172:173]
	v_pk_mul_f32 v[64:65], v[64:65], v[152:153]
	v_pk_mul_f32 v[60:61], v[60:61], v[156:157]
	v_pk_mul_f32 v[56:57], v[56:57], v[160:161]
	v_pk_mul_f32 v[52:53], v[52:53], v[174:175]
	v_pk_mul_f32 v[62:63], v[62:63], v[150:151]
	v_pk_mul_f32 v[58:59], v[58:59], v[154:155]
	v_pk_mul_f32 v[54:55], v[54:55], v[158:159]
	v_pk_mul_f32 v[50:51], v[50:51], v[172:173]
	v_pk_mul_f32 v[48:49], v[48:49], v[152:153]
	v_pk_mul_f32 v[44:45], v[44:45], v[156:157]
	v_pk_mul_f32 v[40:41], v[40:41], v[160:161]
	v_pk_mul_f32 v[36:37], v[36:37], v[174:175]
	v_pk_mul_f32 v[46:47], v[46:47], v[150:151]
	v_pk_mul_f32 v[42:43], v[42:43], v[154:155]
	v_pk_mul_f32 v[38:39], v[38:39], v[158:159]
	v_pk_mul_f32 v[34:35], v[34:35], v[172:173]
	v_pk_mul_f32 v[32:33], v[32:33], v[152:153]
	v_pk_mul_f32 v[28:29], v[28:29], v[156:157]
	v_pk_mul_f32 v[24:25], v[24:25], v[160:161]
	v_pk_mul_f32 v[20:21], v[20:21], v[174:175]
	v_pk_mul_f32 v[30:31], v[30:31], v[150:151]
	v_pk_mul_f32 v[26:27], v[26:27], v[154:155]
	v_pk_mul_f32 v[22:23], v[22:23], v[158:159]
	v_pk_mul_f32 v[18:19], v[18:19], v[172:173]

; __device__ __forceinline__ void finishSM(f32x16& p0, f32x16& p1, float alpha, float& l_reg, bf16x8& pa0, bf16x8& pa1, bf16x8& pa2, bf16x8& pa3) {
; #pragma unroll
;     for (int r = 0; r < 16; ++r) p1[r] = __builtin_amdgcn_exp2f(p1[r]);
;     float ps = 0;
; #pragma unroll
;     for (int r = 0; r < 16; ++r) ps += p0[r];
; #pragma unroll
;     for (int r = 0; r < 16; ++r) ps += p1[r];
;     { auto rr = __builtin_amdgcn_permlane32_swap(__float_as_uint(ps), __float_as_uint(ps), false, false);
;       ps = __uint_as_float(rr[0]) + __uint_as_float(rr[1]); }
;     l_reg = l_reg * alpha + ps;
;     ...
;     PK4(p0, 0, pa0); PK4(p0, 8, pa1); PK4(p1, 0, pa2); PK4(p1, 8, pa3);
; template <int KB>
; __device__ __forceinline__ void qkt(f32x16& p0, f32x16& p1, const char* K_lds, int r32, int hi, const bf16x8* qr) {
;     p0 = f32x16{}; p1 = f32x16{};
;     const char* kb[4];
; #pragma unroll
;     for (int dd = 0; dd < 4; ++dd) kb[dd] = K_lds + KB * SHM_K + KSWZ(r32, (dd * 16 + hi * 8) * 2);
; #pragma unroll
;     for (int d0 = 0; d0 < 8; ++d0) { const char* a = kb[d0 & 3] + (d0 >> 2) * 128;
;         bf16x8 b0 = *reinterpret_cast<const bf16x8*>(a);
;         bf16x8 b1 = *reinterpret_cast<const bf16x8*>(a + 32 * 256);
;         p0 = __builtin_amdgcn_mfma_f32_32x32x16_bf16(b0, qr[d0], p0, 0, 0, 0);
;         p1 = __builtin_amdgcn_mfma_f32_32x32x16_bf16(b1, qr[d0], p1, 0, 0, 0); }
; }
.Lp5_a2:
	ds_read_b128 v[66:69], v199 offset:32768
	ds_read_b128 v[70:73], v199 offset:40960
	ds_read_b128 v[172:175], v200 offset:32768
	ds_read_b128 v[224:227], v200 offset:40960
	ds_read_b128 v[232:235], v201 offset:32768
	ds_read_b128 v[236:239], v201 offset:40960
	ds_read_b128 v[240:243], v202 offset:32768
	ds_read_b128 v[244:247], v202 offset:40960
	v_exp_f32_e32 v211, v211
	v_exp_f32_e32 v212, v212
	s_waitcnt lgkmcnt(7)
	v_mfma_f32_32x32x16_bf16 v[82:97], v[66:69], v[126:129], 0
	v_exp_f32_e32 v213, v213
	v_exp_f32_e32 v214, v214
	v_exp_f32_e32 v215, v215
	s_waitcnt lgkmcnt(6)
	v_mfma_f32_32x32x16_bf16 v[66:81], v[70:73], v[126:129], 0
	v_exp_f32_e32 v216, v216
	v_exp_f32_e32 v207, v207
	s_waitcnt lgkmcnt(5)
	v_mfma_f32_32x32x16_bf16 v[82:97], v[172:175], v[122:125], v[82:97]
	ds_read_b128 v[172:175], v199 offset:32896
	v_exp_f32_e32 v250, v219
	v_exp_f32_e32 v219, v209
	v_add_f32_e32 v209, v147, v146
	s_waitcnt lgkmcnt(5)
	v_mfma_f32_32x32x16_bf16 v[66:81], v[224:227], v[122:125], v[66:81]
	ds_read_b128 v[224:227], v199 offset:41088
	v_add_f32_e32 v209, v148, v209
	v_add_f32_e32 v209, v159, v209
	v_add_f32_e32 v209, v160, v209
	v_add_f32_e32 v209, v161, v209
	v_add_f32_e32 v209, v149, v209
	s_waitcnt lgkmcnt(5)
	v_mfma_f32_32x32x16_bf16 v[82:97], v[232:235], v[118:121], v[82:97]
	ds_read_b128 v[232:235], v200 offset:32896
	v_add_f32_e32 v209, v158, v209
	v_add_f32_e32 v209, v150, v209
	v_add_f32_e32 v209, v151, v209
	v_add_f32_e32 v209, v155, v209
	v_add_f32_e32 v209, v157, v209
	s_waitcnt lgkmcnt(5)
	v_mfma_f32_32x32x16_bf16 v[66:81], v[236:239], v[118:121], v[66:81]
	ds_read_b128 v[236:239], v200 offset:41088
	v_exp_f32_e32 v248, v217
	v_add_f32_e32 v209, v152, v209
	v_exp_f32_e32 v249, v218
	s_waitcnt lgkmcnt(5)
	v_mfma_f32_32x32x16_bf16 v[82:97], v[240:243], v[114:117], v[82:97]
	ds_read_b128 v[240:243], v201 offset:32896
	v_add_f32_e32 v209, v153, v209
	v_add_f32_e32 v209, v154, v209
	v_exp_f32_e32 v251, v220
	v_add_f32_e32 v209, v156, v209
	s_waitcnt lgkmcnt(5)
	v_mfma_f32_32x32x16_bf16 v[66:81], v[244:247], v[114:117], v[66:81]
	ds_read_b128 v[244:247], v201 offset:41088
	v_exp_f32_e32 v217, v221
	v_add_f32_e32 v209, v248, v209
	v_exp_f32_e32 v218, v210
	s_waitcnt lgkmcnt(5)
	v_mfma_f32_32x32x16_bf16 v[82:97], v[172:175], v[110:113], v[82:97]
	ds_read_b128 v[172:175], v202 offset:32896
	v_add_f32_e32 v209, v249, v209
	v_add_f32_e32 v209, v250, v209
	v_add_f32_e32 v209, v251, v209
	v_add_f32_e32 v209, v217, v209
	v_add_f32_e32 v209, v218, v209
	s_waitcnt lgkmcnt(5)
	v_mfma_f32_32x32x16_bf16 v[66:81], v[224:227], v[110:113], v[66:81]
	ds_read_b128 v[224:227], v202 offset:41088
	v_add_f32_e32 v209, v211, v209
	v_add_f32_e32 v209, v212, v209
	v_add_f32_e32 v209, v213, v209
	v_exp_f32_e32 v220, v222
	s_waitcnt lgkmcnt(5)
	v_mfma_f32_32x32x16_bf16 v[82:97], v[232:235], v[106:109], v[82:97]
	v_add_f32_e32 v209, v214, v209
	v_exp_f32_e32 v221, v223
	v_add_f32_e32 v209, v215, v209
	v_add_f32_e32 v209, v216, v209
	s_waitcnt lgkmcnt(4)
	v_mfma_f32_32x32x16_bf16 v[66:81], v[236:239], v[106:109], v[66:81]
	v_add_f32_e32 v209, v219, v209
	v_add_f32_e32 v209, v220, v209
	v_add_f32_e32 v209, v221, v209
	v_add_f32_e32 v209, v207, v209
	s_waitcnt lgkmcnt(3)
	v_mfma_f32_32x32x16_bf16 v[82:97], v[240:243], v[102:105], v[82:97]
	v_cvt_pk_bf16_f32 v146, v146, v147
	v_cvt_pk_bf16_f32 v147, v148, v159
	v_cvt_pk_bf16_f32 v148, v160, v161
	v_cvt_pk_bf16_f32 v149, v149, v158
	v_cvt_pk_bf16_f32 v150, v150, v151
	s_waitcnt lgkmcnt(2)
	v_mfma_f32_32x32x16_bf16 v[66:81], v[244:247], v[102:105], v[66:81]
	v_cvt_pk_bf16_f32 v151, v155, v157
	v_cvt_pk_bf16_f32 v152, v152, v153
	v_cvt_pk_bf16_f32 v153, v154, v156
	v_cvt_pk_bf16_f32 v154, v248, v249
	v_cvt_pk_bf16_f32 v155, v250, v251
	s_waitcnt lgkmcnt(1)
	v_mfma_f32_32x32x16_bf16 v[82:97], v[172:175], v[98:101], v[82:97]
	v_cvt_pk_bf16_f32 v156, v217, v218
	v_cvt_pk_bf16_f32 v157, v211, v212
	v_cvt_pk_bf16_f32 v158, v213, v214
	v_cvt_pk_bf16_f32 v159, v215, v216
	v_cvt_pk_bf16_f32 v160, v219, v220
	s_waitcnt lgkmcnt(0)
	v_mfma_f32_32x32x16_bf16 v[66:81], v[224:227], v[98:101], v[66:81]
	v_cvt_pk_bf16_f32 v161, v221, v207
	s_add_i32 s82, s82, 2
	s_cmp_le_u32 s82, s81
	s_cselect_b64 s[36:37], -1, 0
	s_cmp_gt_u32 s82, s81
	s_cbranch_scc1 .Lp5_skip_ld

; #define SBAR() __builtin_amdgcn_sched_barrier(0)
; #define SLOAD_H(Kp, Vp, k0) do { S.st_v0 = load8(ROW(Vp, k0, sr)); S.st_v1 = load8(ROW(Vp, k0, 32 + sr));              \
;                          S.st_k0 = load8(ROW(Kp, k0, sr)); S.st_k1 = load8(ROW(Kp, k0, 32 + sr)); } while (0)
; __device__ __forceinline__ void finishSM(f32x16& p0, f32x16& p1, float alpha, float& l_reg, bf16x8& pa0, bf16x8& pa1, bf16x8& pa2, bf16x8& pa3) {
; #pragma unroll
;     for (int r = 0; r < 16; ++r) p1[r] = __builtin_amdgcn_exp2f(p1[r]);
;     float ps = 0;
; #pragma unroll
;     for (int r = 0; r < 16; ++r) ps += p0[r];
; #pragma unroll
;     for (int r = 0; r < 16; ++r) ps += p1[r];
;     { auto rr = __builtin_amdgcn_permlane32_swap(__float_as_uint(ps), __float_as_uint(ps), false, false);
;       ps = __uint_as_float(rr[0]) + __uint_as_float(rr[1]); }
;     l_reg = l_reg * alpha + ps;
;     ...
;     PK4(p0, 0, pa0); PK4(p0, 8, pa1); PK4(p1, 0, pa2); PK4(p1, 8, pa3);
; __device__ __forceinline__ void attn_block(const BlockRef& cur, const BlockRef& nxt, char* lds, Seam& S) {
;     ...
;     mw = LDMASK(NT - 1);
;     SBAR(); qkt<1>(pB0, pB1, K_lds, r32, hi, S.qr); SBAR();
;     SLOAD_H(nxt.K, nxt.V, 0); SBAR();
; #pragma unroll
;     for (int d0 = 0; d0 < 8; ++d0) S.qr[d0] = load8(nxt.Q + (size_t)(wid * QBLK + r32) * LD + d0 * 16 + hi * 8);
;     SBAR();
;     finishSM(pA0, pA1, alA, l_reg, pa0, pa1, pa2, pa3); SBAR();
;     pv_tile<0>(o, vb0, pa0, pa1, pa2, pa3);
.LBB0_1313:
	v_mov_b32_e32 v66, v205
	s_nop 1
	v_permlane32_swap_b32_e32 v205, v66
	v_add_f32_e32 v205, v205, v66
	v_lshl_add_u32 v66, s81, 3, v165
	global_load_dwordx2 v[188:189], v66, s[68:69]
	ds_read_b128 v[66:69], v199 offset:49152
	ds_read_b128 v[82:85], v199 offset:49280
	ds_read_b128 v[86:89], v200 offset:49152
	ds_read_b128 v[90:93], v200 offset:49280
	s_waitcnt lgkmcnt(3)
	v_mfma_f32_32x32x16_bf16 v[66:81], v[66:69], v[126:129], 0
	s_waitcnt lgkmcnt(1)
	v_mfma_f32_32x32x16_bf16 v[66:81], v[86:89], v[122:125], v[66:81]
	ds_read_b128 v[86:89], v201 offset:49152
	ds_read_b128 v[94:97], v201 offset:49280
	s_waitcnt lgkmcnt(1)
	v_mfma_f32_32x32x16_bf16 v[66:81], v[86:89], v[118:121], v[66:81]
	ds_read_b128 v[86:89], v202 offset:49152
	ds_read_b128 v[130:133], v202 offset:49280
	s_waitcnt lgkmcnt(1)
	v_mfma_f32_32x32x16_bf16 v[66:81], v[86:89], v[114:117], v[66:81]
	v_mfma_f32_32x32x16_bf16 v[66:81], v[82:85], v[110:113], v[66:81]
	ds_read_b128 v[82:85], v199 offset:57344
	ds_read_b128 v[138:141], v199 offset:57472
	ds_read_b128 v[228:231], v200 offset:57344
	ds_read_b128 v[232:235], v200 offset:57472
	ds_read_b128 v[236:239], v201 offset:57344
	ds_read_b128 v[240:243], v201 offset:57472
	ds_read_b128 v[244:247], v202 offset:57344
	ds_read_b128 v[248:251], v202 offset:57472
	v_mfma_f32_32x32x16_bf16 v[66:81], v[90:93], v[106:109], v[66:81]
	v_mfma_f32_32x32x16_bf16 v[66:81], v[94:97], v[102:105], v[66:81]
	s_waitcnt lgkmcnt(8)
	v_mfma_f32_32x32x16_bf16 v[66:81], v[130:133], v[98:101], v[66:81]
	v_mov_b32_e32 v165, v167
	v_lshl_add_u64 v[86:87], s[62:63], 0, v[164:165]
	v_mov_b32_e32 v177, v167
	v_mov_b32_e32 v179, v167
	v_lshl_add_u64 v[86:87], v[86:87], 0, v[176:177]
	v_lshl_add_u64 v[88:89], s[62:63], 0, v[178:179]
	v_lshl_add_u64 v[88:89], v[88:89], 0, v[176:177]
	global_load_dwordx4 v[130:133], v[86:87], off
	global_load_dwordx4 v[134:137], v[88:89], off
	v_lshl_add_u64 v[86:87], s[60:61], 0, v[164:165]
	v_lshl_add_u64 v[86:87], v[86:87], 0, v[176:177]
	v_lshl_add_u64 v[88:89], s[60:61], 0, v[178:179]
	v_lshl_add_u64 v[88:89], v[88:89], 0, v[176:177]
	global_load_dwordx4 v[142:145], v[86:87], off
	global_load_dwordx4 v[146:149], v[88:89], off
	s_waitcnt lgkmcnt(7)
	v_mfma_f32_32x32x16_bf16 v[82:97], v[82:85], v[126:129], 0
	v_mov_b32_e32 v187, v167
	v_mov_b32_e32 v181, v167
	s_waitcnt lgkmcnt(5)
	v_mfma_f32_32x32x16_bf16 v[82:97], v[228:231], v[122:125], v[82:97]
	s_waitcnt lgkmcnt(3)
	v_mfma_f32_32x32x16_bf16 v[82:97], v[236:239], v[118:121], v[82:97]
	s_waitcnt lgkmcnt(1)
	v_mfma_f32_32x32x16_bf16 v[82:97], v[244:247], v[114:117], v[82:97]
	v_mfma_f32_32x32x16_bf16 v[82:97], v[138:141], v[110:113], v[82:97]
	v_lshlrev_b64 v[110:111], 11, v[186:187]
	v_lshl_add_u64 v[110:111], s[10:11], 0, v[110:111]
	v_lshl_add_u64 v[138:139], v[110:111], 0, v[180:181]
	v_mfma_f32_32x32x16_bf16 v[82:97], v[232:235], v[106:109], v[82:97]
	global_load_dwordx4 v[126:129], v[138:139], off
	global_load_dwordx4 v[122:125], v[138:139], off offset:32
	global_load_dwordx4 v[118:121], v[138:139], off offset:64
	global_load_dwordx4 v[114:117], v[138:139], off offset:96
	global_load_dwordx4 v[110:113], v[138:139], off offset:128
	global_load_dwordx4 v[106:109], v[138:139], off offset:160
	v_mfma_f32_32x32x16_bf16 v[82:97], v[240:243], v[102:105], v[82:97]
	global_load_dwordx4 v[102:105], v[138:139], off offset:192
	s_nop 0
	global_load_dwordx4 v[138:141], v[138:139], off offset:224
	s_waitcnt lgkmcnt(0)
	v_mfma_f32_32x32x16_bf16 v[82:97], v[248:251], v[98:101], v[82:97]
	v_add_f32_e32 v98, 0, v219
	v_add_f32_e32 v98, v220, v98
	v_add_f32_e32 v98, v221, v98
	v_add_f32_e32 v98, v222, v98
	v_add_f32_e32 v98, v223, v98
	v_add_f32_e32 v98, v225, v98
	v_add_f32_e32 v98, v224, v98
	v_add_f32_e32 v98, v226, v98
	v_add_f32_e32 v98, v211, v98
	v_add_f32_e32 v98, v212, v98
	v_add_f32_e32 v98, v213, v98
	v_add_f32_e32 v98, v215, v98
	v_exp_f32_e32 v100, v194
	v_add_f32_e32 v98, v214, v98
	v_exp_f32_e32 v101, v195
	v_add_f32_e32 v98, v216, v98
	v_exp_f32_e32 v165, v192
	v_add_f32_e32 v98, v217, v98
	v_exp_f32_e32 v172, v193
	v_add_f32_e32 v98, v218, v98
	v_exp_f32_e32 v173, v158
	v_add_f32_e32 v98, v100, v98
	v_exp_f32_e32 v174, v159
	v_add_f32_e32 v98, v101, v98
	v_exp_f32_e32 v175, v154
	v_add_f32_e32 v98, v165, v98
	v_exp_f32_e32 v177, v155
	v_add_f32_e32 v98, v172, v98
	v_exp_f32_e32 v179, v150
	v_add_f32_e32 v98, v173, v98
	v_exp_f32_e32 v181, v151
	v_add_f32_e32 v98, v174, v98
	v_exp_f32_e32 v186, v160
	v_add_f32_e32 v98, v175, v98
	v_exp_f32_e32 v187, v161
	v_add_f32_e32 v98, v177, v98
	v_exp_f32_e32 v192, v156
	v_add_f32_e32 v98, v179, v98
	v_exp_f32_e32 v193, v157
	v_add_f32_e32 v98, v181, v98
	v_exp_f32_e32 v194, v152
	v_add_f32_e32 v98, v186, v98
	v_exp_f32_e32 v195, v153
	v_add_f32_e32 v98, v187, v98
	v_add_f32_e32 v98, v192, v98
	v_add_f32_e32 v98, v193, v98
	v_add_f32_e32 v98, v194, v98
	v_add_f32_e32 v98, v98, v195
	v_mov_b32_e32 v99, v98
	v_cvt_pk_bf16_f32 v150, v219, v220
	v_cvt_pk_bf16_f32 v151, v221, v222
	v_cvt_pk_bf16_f32 v152, v223, v225
	v_cvt_pk_bf16_f32 v153, v224, v226
	v_permlane32_swap_b32_e32 v98, v99
	v_cvt_pk_bf16_f32 v154, v211, v212
	v_cvt_pk_bf16_f32 v155, v213, v215
	v_cvt_pk_bf16_f32 v156, v214, v216
	v_cvt_pk_bf16_f32 v157, v217, v218
	v_cvt_pk_bf16_f32 v158, v100, v101
	v_cvt_pk_bf16_f32 v159, v165, v172
	v_cvt_pk_bf16_f32 v160, v173, v174
	v_cvt_pk_bf16_f32 v161, v175, v177
	v_cvt_pk_bf16_f32 v190, v179, v181
	v_cvt_pk_bf16_f32 v191, v186, v187
	v_cvt_pk_bf16_f32 v192, v192, v193
	v_cvt_pk_bf16_f32 v193, v194, v195
	ds_read_b64_tr_b16 v[208:209], v1 offset:0
	ds_read_b64_tr_b16 v[210:211], v1 offset:0x800
	ds_read_b64_tr_b16 v[212:213], v1 offset:0x1000
	ds_read_b64_tr_b16 v[214:215], v1 offset:0x1800
	ds_read_b64_tr_b16 v[216:217], v1 offset:0x2000
	ds_read_b64_tr_b16 v[218:219], v1 offset:0x2800
	ds_read_b64_tr_b16 v[220:221], v1 offset:0x3000
	ds_read_b64_tr_b16 v[222:223], v1 offset:0x3800
	s_waitcnt lgkmcnt(0)
; __device__ __forceinline__ void sel_mask_tile(f32x16& p0, f32x16& p1, unsigned wlo, unsigned whi, int hi) {
;     const unsigned NEGB = 0xff800000u;
;     const unsigned lo = wlo >> (4 * hi), h2 = whi >> (4 * hi);
; #pragma unroll
;     for (int r = 0; r < 16; ++r) {
;         const int c = (r & 3) + 8 * (r >> 2);
;         const unsigned m0 = (unsigned)__builtin_amdgcn_sbfe((int)lo, c, 1), m1 = (unsigned)__builtin_amdgcn_sbfe((int)h2, c, 1);
;         p0[r] = __uint_as_float((__float_as_uint(p0[r]) & m0) | (NEGB & ~m0));
;         p1[r] = __uint_as_float((__float_as_uint(p1[r]) & m1) | (NEGB & ~m1));
;     }
; }
; __device__ __forceinline__ void partialSM(f32x16& p0, f32x16& p1, float& m_reg, float& mn, float& alpha) {
;     float pmax = p0[0];
; #pragma unroll
;     for (int r = 1; r < 16; ++r) pmax = fmaxf(pmax, p0[r]);
; #pragma unroll
;     for (int r = 0; r < 16; ++r) pmax = fmaxf(pmax, p1[r]);
;     { auto rr = __builtin_amdgcn_permlane32_swap(__float_as_uint(pmax), __float_as_uint(pmax), false, false);
;       pmax = fmaxf(__uint_as_float(rr[0]), __uint_as_float(rr[1])); }
;     constexpr float C2 = 1.4426950408889634f * SCALE;
;     if (__builtin_expect(__all((pmax - m_reg) * SCALE <= THR), 1)) { mn = m_reg; alpha = 1.f; }
;     else { mn = fmaxf(m_reg, pmax); alpha = __builtin_amdgcn_exp2f((m_reg - mn) * C2); m_reg = mn; }
; template <int VB>
; __device__ __forceinline__ void pv_tile(f32x16* o, int vb0, bf16x8 pa0, bf16x8 pa1, bf16x8 pa2, bf16x8 pa3) {
;     ...
;     PV_D0(0); PV_D0(1); PV_D0(2); PV_D0(3);
	s_nop 0
	v_mfma_f32_32x32x16_bf16 v[2:17], v[150:153], v[208:211], v[2:17]
	ds_read_b64_tr_b16 v[208:209], v1 offset:0x200
	ds_read_b64_tr_b16 v[210:211], v1 offset:0xa00
	v_mfma_f32_32x32x16_bf16 v[2:17], v[154:157], v[212:215], v[2:17]
	ds_read_b64_tr_b16 v[212:213], v1 offset:0x1200
	ds_read_b64_tr_b16 v[214:215], v1 offset:0x1a00
	v_mfma_f32_32x32x16_bf16 v[2:17], v[158:161], v[216:219], v[2:17]
	ds_read_b64_tr_b16 v[216:217], v1 offset:0x2200
	ds_read_b64_tr_b16 v[218:219], v1 offset:0x2a00
	ds_read_b64_tr_b16 v[224:225], v1 offset:0x3200
	ds_read_b64_tr_b16 v[226:227], v1 offset:0x3a00
	s_waitcnt lgkmcnt(0)
	v_mfma_f32_32x32x16_bf16 v[2:17], v[190:193], v[220:223], v[2:17]
	v_mfma_f32_32x32x16_bf16 v[50:65], v[150:153], v[208:211], v[50:65]
	ds_read_b64_tr_b16 v[208:209], v1 offset:0x400
	ds_read_b64_tr_b16 v[210:211], v1 offset:0xc00
	v_mfma_f32_32x32x16_bf16 v[50:65], v[154:157], v[212:215], v[50:65]
	ds_read_b64_tr_b16 v[212:213], v1 offset:0x1400
	ds_read_b64_tr_b16 v[214:215], v1 offset:0x1c00
	v_mfma_f32_32x32x16_bf16 v[50:65], v[158:161], v[216:219], v[50:65]
	ds_read_b64_tr_b16 v[216:217], v1 offset:0x2400
	ds_read_b64_tr_b16 v[218:219], v1 offset:0x2c00
	ds_read_b64_tr_b16 v[220:221], v1 offset:0x3400
	ds_read_b64_tr_b16 v[222:223], v1 offset:0x3c00
	s_waitcnt lgkmcnt(0)
	v_mfma_f32_32x32x16_bf16 v[50:65], v[190:193], v[224:227], v[50:65]
	v_mfma_f32_32x32x16_bf16 v[34:49], v[150:153], v[208:211], v[34:49]
	ds_read_b64_tr_b16 v[208:209], v1 offset:0x600
	ds_read_b64_tr_b16 v[210:211], v1 offset:0xe00
	v_mfma_f32_32x32x16_bf16 v[34:49], v[154:157], v[212:215], v[34:49]
	ds_read_b64_tr_b16 v[212:213], v1 offset:0x1600
	ds_read_b64_tr_b16 v[214:215], v1 offset:0x1e00
	v_mfma_f32_32x32x16_bf16 v[34:49], v[158:161], v[216:219], v[34:49]
	ds_read_b64_tr_b16 v[216:217], v1 offset:0x2600
	ds_read_b64_tr_b16 v[218:219], v1 offset:0x2e00
	ds_read_b64_tr_b16 v[224:225], v1 offset:0x3600
	ds_read_b64_tr_b16 v[226:227], v1 offset:0x3e00
	s_waitcnt lgkmcnt(0)
	v_mfma_f32_32x32x16_bf16 v[34:49], v[190:193], v[220:223], v[34:49]
	s_waitcnt vmcnt(12)
	v_lshrrev_b32_e32 v165, v163, v188
	v_lshrrev_b32_e32 v172, v163, v189
	v_bfe_i32 v100, v165, 0, 1
	v_bfe_i32 v101, v172, 0, 1
	v_bitop3_b32 v100, v66, s74, v100 bitop3:0xe4
	v_bfe_i32 v66, v165, 1, 1
	v_bitop3_b32 v82, v82, s74, v101 bitop3:0xe4
	v_mfma_f32_32x32x16_bf16 v[18:33], v[150:153], v[208:211], v[18:33]
	v_bfe_i32 v150, v172, 1, 1
	v_bitop3_b32 v101, v67, s74, v66 bitop3:0xe4
	v_bfe_i32 v66, v165, 2, 1
	v_bitop3_b32 v67, v83, s74, v150 bitop3:0xe4
	v_bfe_i32 v150, v172, 2, 1
	v_bitop3_b32 v83, v68, s74, v66 bitop3:0xe4
	v_bfe_i32 v66, v165, 3, 1
	v_bitop3_b32 v68, v84, s74, v150 bitop3:0xe4
	v_bfe_i32 v84, v172, 3, 1
	v_bitop3_b32 v150, v69, s74, v66 bitop3:0xe4
	v_bfe_i32 v66, v165, 8, 1
	v_bitop3_b32 v69, v85, s74, v84 bitop3:0xe4
	v_bfe_i32 v84, v172, 8, 1
	v_bitop3_b32 v151, v70, s74, v66 bitop3:0xe4
	v_bfe_i32 v66, v165, 9, 1
	v_bitop3_b32 v70, v86, s74, v84 bitop3:0xe4
	v_bfe_i32 v84, v172, 9, 1
	v_bitop3_b32 v152, v71, s74, v66 bitop3:0xe4
	v_bfe_i32 v66, v165, 10, 1
	v_bitop3_b32 v71, v87, s74, v84 bitop3:0xe4
	v_bfe_i32 v84, v172, 10, 1
	v_bitop3_b32 v87, v72, s74, v66 bitop3:0xe4
	v_bfe_i32 v66, v165, 11, 1
	v_bitop3_b32 v72, v88, s74, v84 bitop3:0xe4
	v_bfe_i32 v84, v172, 11, 1
	v_bitop3_b32 v88, v73, s74, v66 bitop3:0xe4
	v_bfe_i32 v66, v165, 16, 1
	v_bitop3_b32 v84, v89, s74, v84 bitop3:0xe4
	v_bfe_i32 v73, v172, 16, 1
	v_bitop3_b32 v89, v74, s74, v66 bitop3:0xe4
	v_bfe_i32 v66, v165, 17, 1
	v_bitop3_b32 v85, v90, s74, v73 bitop3:0xe4
	v_bfe_i32 v73, v172, 17, 1
	v_bitop3_b32 v90, v75, s74, v66 bitop3:0xe4
	v_bfe_i32 v66, v165, 18, 1
	v_bitop3_b32 v86, v91, s74, v73 bitop3:0xe4
	v_bfe_i32 v73, v172, 18, 1
	v_bitop3_b32 v91, v76, s74, v66 bitop3:0xe4
	v_bfe_i32 v66, v165, 19, 1
	v_bitop3_b32 v76, v92, s74, v73 bitop3:0xe4
	v_bfe_i32 v73, v172, 19, 1
	v_bitop3_b32 v92, v77, s74, v66 bitop3:0xe4
	v_bfe_i32 v66, v165, 24, 1
	v_bitop3_b32 v77, v93, s74, v73 bitop3:0xe4
	v_bitop3_b32 v93, v78, s74, v66 bitop3:0xe4
	v_bfe_i32 v66, v165, 25, 1
	v_bitop3_b32 v79, v79, s74, v66 bitop3:0xe4
	v_bfe_i32 v66, v165, 26, 1
	v_bfe_i32 v73, v172, 24, 1
	v_bitop3_b32 v80, v80, s74, v66 bitop3:0xe4
	v_bfe_i32 v66, v165, 27, 1
	v_bitop3_b32 v78, v94, s74, v73 bitop3:0xe4
	v_bitop3_b32 v81, v81, s74, v66 bitop3:0xe4
	v_max_f32_e32 v66, v101, v101
	v_max_f32_e32 v94, v100, v100
	v_max_f32_e32 v66, v94, v66
	v_max3_f32 v66, v66, v83, v150
	v_max3_f32 v66, v66, v151, v152
	v_max3_f32 v66, v66, v87, v88
	v_max3_f32 v66, v66, v89, v90
	v_max3_f32 v66, v66, v91, v92
	v_max3_f32 v66, v66, v93, v79
	v_mfma_f32_32x32x16_bf16 v[18:33], v[154:157], v[212:215], v[18:33]
	v_max3_f32 v66, v66, v80, v81
	v_max3_f32 v66, v66, v82, v67
	v_max3_f32 v66, v66, v68, v69
	v_max3_f32 v66, v66, v70, v71
	v_max3_f32 v66, v66, v72, v84
	v_bfe_i32 v73, v172, 25, 1
	v_max3_f32 v66, v66, v85, v86
	v_bitop3_b32 v73, v95, s74, v73 bitop3:0xe4
	v_bfe_i32 v74, v172, 26, 1
	v_bfe_i32 v75, v172, 27, 1
	v_max3_f32 v66, v66, v76, v77
	v_bitop3_b32 v74, v96, s74, v74 bitop3:0xe4
	v_bitop3_b32 v75, v97, s74, v75 bitop3:0xe4
	v_max3_f32 v66, v66, v78, v73
	v_mfma_f32_32x32x16_bf16 v[18:33], v[158:161], v[216:219], v[18:33]
	v_max3_f32 v66, v66, v74, v75
	v_mov_b32_e32 v94, v66
	s_nop 1
	v_permlane32_swap_b32_e32 v66, v94
	v_max_f32_e32 v94, v94, v94
	v_max_f32_e32 v66, v66, v66
	v_max_f32_e32 v66, v66, v94
	v_sub_f32_e32 v94, v66, v206
	v_mul_f32_e32 v95, 0x3db504f3, v94
	v_max_f32_e32 v94, v206, v206
	v_max_f32_e32 v94, v94, v66
	v_mfma_f32_32x32x16_bf16 v[18:33], v[190:193], v[224:227], v[18:33]
	v_sub_f32_e32 v66, v206, v94
	v_mul_f32_e32 v66, 0x3e0293ee, v66
	v_exp_f32_e32 v66, v66
	v_cmp_ge_f32_e32 vcc, s75, v95
	s_cmp_eq_u64 vcc, exec
	s_cselect_b64 s[6:7], -1, 0
	v_cndmask_b32_e64 v66, v66, 1.0, s[6:7]
	v_cmp_gt_f32_e32 vcc, 1.0, v66
	s_barrier
; #define SBAR() __builtin_amdgcn_sched_barrier(0)
; #define RESC(a) do { if (__any((a) < 1.f)) { if (hi == 0) al_l[r32] = (a); asm volatile("s_waitcnt lgkmcnt(0)" ::: "memory");              \
;                      for (int d_ = 0; d_ < 4; ++d_) for (int r = 0; r < 16; ++r) o[d_][r] *= al_l[crow(r, hi)]; } } while (0)
; #define MASKT(P0_, P1_) sel_mask_tile(P0_, P1_, mw.x, mw.y, hi)
; __device__ __forceinline__ void finishSM(f32x16& p0, f32x16& p1, float alpha, float& l_reg, bf16x8& pa0, bf16x8& pa1, bf16x8& pa2, bf16x8& pa3) {
; #pragma unroll
;     for (int r = 0; r < 16; ++r) p1[r] = __builtin_amdgcn_exp2f(p1[r]);
;     float ps = 0;
; #pragma unroll
;     for (int r = 0; r < 16; ++r) ps += p0[r];
; #pragma unroll
;     for (int r = 0; r < 16; ++r) ps += p1[r];
;     { auto rr = __builtin_amdgcn_permlane32_swap(__float_as_uint(ps), __float_as_uint(ps), false, false);
;       ps = __uint_as_float(rr[0]) + __uint_as_float(rr[1]); }
;     l_reg = l_reg * alpha + ps;
;     ...
;     PK4(p0, 0, pa0); PK4(p0, 8, pa1); PK4(p1, 0, pa2); PK4(p1, 8, pa3);
; __device__ __forceinline__ void attn_block(const BlockRef& cur, const BlockRef& nxt, char* lds, Seam& S) {
;     ...
;     MASKT(pB0, pB1); partialSM(pB0, pB1, m_reg, mnB, alB); __syncthreads(); RESC(alB);
;     finishSM(pB0, pB1, alB, l_reg, pa0, pa1, pa2, pa3); SBAR(); pv_tile<1>(o, vb0, pa0, pa1, pa2, pa3);
	s_cbranch_vccz .LBB0_1317
	s_and_saveexec_b64 s[36:37], s[0:1]
	ds_write_b32 v185, v66 offset:128
	s_or_b64 exec, exec, s[36:37]
	s_waitcnt lgkmcnt(0)
	ds_read_b128 v[154:157], v183 offset:224
	ds_read_b128 v[158:161], v183 offset:192
	ds_read_b128 v[172:175], v183 offset:160
	ds_read_b128 v[186:189], v183 offset:128
	s_waitcnt lgkmcnt(3)
	v_pk_mul_f32 v[16:17], v[16:17], v[156:157]
	s_waitcnt lgkmcnt(2)
	v_pk_mul_f32 v[12:13], v[12:13], v[160:161]
	s_waitcnt lgkmcnt(1)
	v_pk_mul_f32 v[8:9], v[8:9], v[174:175]
	s_waitcnt lgkmcnt(0)
	v_pk_mul_f32 v[4:5], v[4:5], v[188:189]
	v_pk_mul_f32 v[14:15], v[14:15], v[154:155]
	v_pk_mul_f32 v[10:11], v[10:11], v[158:159]
	v_pk_mul_f32 v[6:7], v[6:7], v[172:173]
	v_pk_mul_f32 v[2:3], v[2:3], v[186:187]
	v_pk_mul_f32 v[64:65], v[64:65], v[156:157]
	v_pk_mul_f32 v[60:61], v[60:61], v[160:161]
	v_pk_mul_f32 v[56:57], v[56:57], v[174:175]
	v_pk_mul_f32 v[52:53], v[52:53], v[188:189]
	v_pk_mul_f32 v[62:63], v[62:63], v[154:155]
	v_pk_mul_f32 v[58:59], v[58:59], v[158:159]
	v_pk_mul_f32 v[54:55], v[54:55], v[172:173]
	v_pk_mul_f32 v[50:51], v[50:51], v[186:187]
	v_pk_mul_f32 v[48:49], v[48:49], v[156:157]
	v_pk_mul_f32 v[44:45], v[44:45], v[160:161]
	v_pk_mul_f32 v[40:41], v[40:41], v[174:175]
	v_pk_mul_f32 v[36:37], v[36:37], v[188:189]
	v_pk_mul_f32 v[46:47], v[46:47], v[154:155]
	v_pk_mul_f32 v[42:43], v[42:43], v[158:159]
	v_pk_mul_f32 v[38:39], v[38:39], v[172:173]
	v_pk_mul_f32 v[34:35], v[34:35], v[186:187]
	v_pk_mul_f32 v[32:33], v[32:33], v[156:157]
	v_pk_mul_f32 v[28:29], v[28:29], v[160:161]
	v_pk_mul_f32 v[24:25], v[24:25], v[174:175]
	v_pk_mul_f32 v[20:21], v[20:21], v[188:189]
	v_pk_mul_f32 v[30:31], v[30:31], v[154:155]
	v_pk_mul_f32 v[26:27], v[26:27], v[158:159]
	v_pk_mul_f32 v[22:23], v[22:23], v[172:173]
	v_pk_mul_f32 v[18:19], v[18:19], v[186:187]
.LBB0_1317:
	v_cndmask_b32_e64 v94, v94, v206, s[6:7]
	v_mul_f32_e32 v94, 0xbe0293ee, v94
	v_fmamk_f32 v153, v100, 0x3e0293ee, v94
	v_fmamk_f32 v154, v101, 0x3e0293ee, v94
	v_fmamk_f32 v161, v80, 0x3e0293ee, v94
	v_exp_f32_e32 v80, v153
	v_fmamk_f32 v83, v83, 0x3e0293ee, v94
	v_fmamk_f32 v165, v81, 0x3e0293ee, v94
	v_exp_f32_e32 v81, v154
	v_fmamk_f32 v150, v150, 0x3e0293ee, v94
	v_fmamk_f32 v155, v88, 0x3e0293ee, v94
	v_fmamk_f32 v88, v82, 0x3e0293ee, v94
	v_exp_f32_e32 v82, v83
	v_fmamk_f32 v151, v151, 0x3e0293ee, v94
	v_fmamk_f32 v67, v67, 0x3e0293ee, v94
	v_exp_f32_e32 v83, v150
	v_fmamk_f32 v152, v152, 0x3e0293ee, v94
	v_fmamk_f32 v87, v87, 0x3e0293ee, v94
	v_fmamk_f32 v156, v89, 0x3e0293ee, v94
	v_fmamk_f32 v157, v90, 0x3e0293ee, v94
	v_fmamk_f32 v158, v91, 0x3e0293ee, v94
	v_fmamk_f32 v159, v92, 0x3e0293ee, v94
	v_fmamk_f32 v160, v93, 0x3e0293ee, v94
	v_fmamk_f32 v79, v79, 0x3e0293ee, v94
	v_fmamk_f32 v68, v68, 0x3e0293ee, v94
	v_fmamk_f32 v89, v69, 0x3e0293ee, v94
	v_fmamk_f32 v90, v70, 0x3e0293ee, v94
	v_fmamk_f32 v91, v71, 0x3e0293ee, v94
	v_fmamk_f32 v92, v72, 0x3e0293ee, v94
	v_fmamk_f32 v93, v84, 0x3e0293ee, v94
	v_fmamk_f32 v95, v85, 0x3e0293ee, v94
	v_fmamk_f32 v96, v86, 0x3e0293ee, v94
	v_fmamk_f32 v97, v76, 0x3e0293ee, v94
	v_fmamk_f32 v100, v77, 0x3e0293ee, v94
	v_fmamk_f32 v101, v78, 0x3e0293ee, v94
	v_exp_f32_e32 v84, v151
	v_fmamk_f32 v73, v73, 0x3e0293ee, v94
	v_fmamk_f32 v74, v74, 0x3e0293ee, v94
	v_fmac_f32_e32 v94, 0x3e0293ee, v75
	v_exp_f32_e32 v75, v88
	v_exp_f32_e32 v88, v67
	v_add_f32_e32 v67, 0, v80
	v_exp_f32_e32 v85, v152
	v_add_f32_e32 v67, v81, v67
	v_exp_f32_e32 v86, v87
	v_add_f32_e32 v67, v82, v67
	v_exp_f32_e32 v87, v155
	v_add_f32_e32 v67, v83, v67
	v_exp_f32_e32 v69, v156
	v_add_f32_e32 v67, v84, v67
	v_exp_f32_e32 v70, v157
	v_add_f32_e32 v67, v85, v67
	v_exp_f32_e32 v71, v158
	v_add_f32_e32 v67, v86, v67
	v_exp_f32_e32 v72, v159
	v_add_f32_e32 v67, v87, v67
	v_exp_f32_e32 v76, v160
	v_add_f32_e32 v67, v69, v67
	v_exp_f32_e32 v77, v79
	v_add_f32_e32 v67, v70, v67
	v_exp_f32_e32 v78, v161
	v_add_f32_e32 v67, v71, v67
	v_exp_f32_e32 v79, v165
	v_add_f32_e32 v67, v72, v67
	v_add_f32_e32 v67, v76, v67
	v_add_f32_e32 v67, v77, v67
	v_exp_f32_e32 v150, v68
	v_add_f32_e32 v67, v78, v67
	v_exp_f32_e32 v89, v89
	v_add_f32_e32 v67, v79, v67
	v_exp_f32_e32 v90, v90
	v_add_f32_e32 v67, v75, v67
	v_exp_f32_e32 v91, v91
	v_add_f32_e32 v67, v88, v67
	v_exp_f32_e32 v92, v92
	v_add_f32_e32 v67, v150, v67
	v_exp_f32_e32 v93, v93
	v_add_f32_e32 v67, v89, v67
	v_exp_f32_e32 v95, v95
	v_add_f32_e32 v67, v90, v67
	v_exp_f32_e32 v96, v96
	v_add_f32_e32 v67, v91, v67
	v_exp_f32_e32 v97, v97
	v_add_f32_e32 v67, v92, v67
	v_exp_f32_e32 v100, v100
	v_add_f32_e32 v67, v93, v67
	v_exp_f32_e32 v101, v101
	v_add_f32_e32 v67, v95, v67
	v_exp_f32_e32 v151, v73
	v_add_f32_e32 v67, v96, v67
	v_exp_f32_e32 v152, v74
	v_add_f32_e32 v67, v97, v67
	v_exp_f32_e32 v94, v94
	v_add_f32_e32 v67, v100, v67
	v_add_f32_e32 v67, v101, v67
	v_add_f32_e32 v67, v151, v67
	v_add_f32_e32 v67, v152, v67
	v_add_f32_e32 v67, v94, v67
	v_mov_b32_e32 v68, v67
	s_nop 1
	v_permlane32_swap_b32_e32 v67, v68
	v_cvt_pk_bf16_f32 v80, v80, v81
	v_cvt_pk_bf16_f32 v81, v82, v83
	v_cvt_pk_bf16_f32 v82, v84, v85
	v_cvt_pk_bf16_f32 v83, v86, v87
	v_cvt_pk_bf16_f32 v70, v69, v70
	v_cvt_pk_bf16_f32 v71, v71, v72
	v_cvt_pk_bf16_f32 v72, v76, v77
	v_cvt_pk_bf16_f32 v73, v78, v79
	v_cvt_pk_bf16_f32 v74, v75, v88
	v_cvt_pk_bf16_f32 v75, v150, v89
	v_cvt_pk_bf16_f32 v76, v90, v91
	v_cvt_pk_bf16_f32 v77, v92, v93
	v_cvt_pk_bf16_f32 v84, v95, v96
	v_cvt_pk_bf16_f32 v85, v97, v100
	v_cvt_pk_bf16_f32 v86, v101, v151
	v_cvt_pk_bf16_f32 v87, v152, v94
	ds_read_b64_tr_b16 v[88:89], v1 offset:0x4000
	ds_read_b64_tr_b16 v[90:91], v1 offset:0x4800
	ds_read_b64_tr_b16 v[92:93], v1 offset:0x5000
	ds_read_b64_tr_b16 v[94:95], v1 offset:0x5800
	ds_read_b64_tr_b16 v[150:151], v1 offset:0x6000
	ds_read_b64_tr_b16 v[152:153], v1 offset:0x6800
	ds_read_b64_tr_b16 v[154:155], v1 offset:0x7000
	ds_read_b64_tr_b16 v[156:157], v1 offset:0x7800
	s_waitcnt lgkmcnt(0)
; #define SBAR() __builtin_amdgcn_sched_barrier(0)
; __device__ __forceinline__ int crow(int r, int hi) { return (r & 3) + 8 * (r >> 2) + 4 * hi; }
; __device__ __forceinline__ unsigned cvtpk(float lo, float hi) { return pg8::cvt_pk_bf16(lo, hi); }
; #define SEAM_K0() do { VMWN(NQL); SWRITE_HK(0); SBAR(); } while (0)
; __device__ __forceinline__ void attn_block(const BlockRef& cur, const BlockRef& nxt, char* lds, Seam& S) {
;     ...
;     finishSM(pB0, pB1, alB, l_reg, pa0, pa1, pa2, pa3); SBAR(); pv_tile<1>(o, vb0, pa0, pa1, pa2, pa3);
;     SBAR(); SEAM_K0();
;     if (hi == 0) li_l[r32] = l_reg; asm volatile("s_waitcnt lgkmcnt(0)" ::: "memory");
;     float rli[16];
; #pragma unroll
;     for (int r = 0; r < 16; ++r) rli[r] = __builtin_amdgcn_rcpf(li_l[crow(r, hi)]);
;     bf16* Ow = cur.O + (size_t)(wid * QBLK) * LD;
; #pragma unroll
;     for (int r = 0; r < 16; ++r) { const int orow = crow(r, hi);
; #pragma unroll
;         for (int d0 = 0; d0 < 4; ++d0) { const float v = o[d0][r] * rli[r];
;             const float vn = __shfl_xor(v, 1);
;             if ((r32 & 1) == 0) *(unsigned*)(Ow + (size_t)orow * LD + d0 * 32 + r32) = cvtpk(v, vn); } }
	s_nop 0
	v_mfma_f32_32x32x16_bf16 v[2:17], v[80:83], v[88:91], v[2:17]
	ds_read_b64_tr_b16 v[88:89], v1 offset:0x4200
	ds_read_b64_tr_b16 v[90:91], v1 offset:0x4a00
	v_mfma_f32_32x32x16_bf16 v[2:17], v[70:73], v[92:95], v[2:17]
	ds_read_b64_tr_b16 v[92:93], v1 offset:0x5200
	ds_read_b64_tr_b16 v[94:95], v1 offset:0x5a00
	v_mfma_f32_32x32x16_bf16 v[2:17], v[74:77], v[150:153], v[2:17]
	ds_read_b64_tr_b16 v[150:151], v1 offset:0x6200
	ds_read_b64_tr_b16 v[152:153], v1 offset:0x6a00
	ds_read_b64_tr_b16 v[158:159], v1 offset:0x7200
	ds_read_b64_tr_b16 v[160:161], v1 offset:0x7a00
	s_waitcnt lgkmcnt(0)
	v_mfma_f32_32x32x16_bf16 v[2:17], v[84:87], v[154:157], v[2:17]
	v_mfma_f32_32x32x16_bf16 v[50:65], v[80:83], v[88:91], v[50:65]
	ds_read_b64_tr_b16 v[88:89], v1 offset:0x4400
	ds_read_b64_tr_b16 v[90:91], v1 offset:0x4c00
	v_mfma_f32_32x32x16_bf16 v[50:65], v[70:73], v[92:95], v[50:65]
	ds_read_b64_tr_b16 v[92:93], v1 offset:0x5400
	ds_read_b64_tr_b16 v[94:95], v1 offset:0x5c00
	v_mfma_f32_32x32x16_bf16 v[50:65], v[74:77], v[150:153], v[50:65]
	ds_read_b64_tr_b16 v[150:151], v1 offset:0x6400
	ds_read_b64_tr_b16 v[152:153], v1 offset:0x6c00
	ds_read_b64_tr_b16 v[154:155], v1 offset:0x7400
	ds_read_b64_tr_b16 v[156:157], v1 offset:0x7c00
	s_waitcnt lgkmcnt(0)
	v_mfma_f32_32x32x16_bf16 v[50:65], v[84:87], v[158:161], v[50:65]
	v_mfma_f32_32x32x16_bf16 v[34:49], v[80:83], v[88:91], v[34:49]
	ds_read_b64_tr_b16 v[88:89], v1 offset:0x4600
	ds_read_b64_tr_b16 v[90:91], v1 offset:0x4e00
	v_mfma_f32_32x32x16_bf16 v[34:49], v[70:73], v[92:95], v[34:49]
	ds_read_b64_tr_b16 v[92:93], v1 offset:0x5600
	ds_read_b64_tr_b16 v[94:95], v1 offset:0x5e00
	v_mfma_f32_32x32x16_bf16 v[34:49], v[74:77], v[150:153], v[34:49]
	ds_read_b64_tr_b16 v[150:151], v1 offset:0x6600
	ds_read_b64_tr_b16 v[152:153], v1 offset:0x6e00
	ds_read_b64_tr_b16 v[158:159], v1 offset:0x7600
	ds_read_b64_tr_b16 v[160:161], v1 offset:0x7e00
	s_waitcnt lgkmcnt(0)
	v_mfma_f32_32x32x16_bf16 v[34:49], v[84:87], v[154:157], v[34:49]
	v_mfma_f32_32x32x16_bf16 v[18:33], v[80:83], v[88:91], v[18:33]
	v_mfma_f32_32x32x16_bf16 v[18:33], v[70:73], v[92:95], v[18:33]
	v_mfma_f32_32x32x16_bf16 v[18:33], v[74:77], v[150:153], v[18:33]
	v_mfma_f32_32x32x16_bf16 v[18:33], v[84:87], v[158:161], v[18:33]
	s_waitcnt vmcnt(8)
	s_waitcnt vmcnt(9)
	ds_write_b128 v204, v[142:145] offset:32768
	s_waitcnt vmcnt(8)
	ds_write_b128 v204, v[146:149] offset:40960
	s_and_saveexec_b64 s[6:7], s[0:1]
	v_add_f32_e32 v69, v98, v99
	v_fmac_f32_e32 v69, v205, v207
	v_add_f32_e32 v67, v67, v68
	v_fmac_f32_e32 v67, v69, v66
	ds_write_b32 v185, v67
	s_or_b64 exec, exec, s[6:7]
	s_waitcnt lgkmcnt(0)
	ds_read_b128 v[78:81], v183
	ds_read_b128 v[74:77], v183 offset:32
	ds_read_b128 v[70:73], v183 offset:64
	ds_read_b128 v[66:69], v183 offset:96
	s_lshl_b64 s[6:7], s[12:13], 11
	s_add_u32 s6, s66, s6
	s_addc_u32 s7, s67, s7
	v_mov_b32_e32 v84, 0x7fe
	v_cndmask_b32_e64 v84, v84, 0, s[4:5]
	v_add3_u32 v82, v166, v168, v84
	v_mov_b32_e32 v84, 0x3020706
	v_mov_b32_e32 v85, 0x5040100
	v_cndmask_b32_e64 v84, v84, v85, s[4:5]
	s_waitcnt lgkmcnt(0)
	v_rcp_f32_e32 v78, v78
	v_rcp_f32_e32 v79, v79
	v_rcp_f32_e32 v80, v80
	v_rcp_f32_e32 v81, v81
	v_rcp_f32_e32 v74, v74
	v_rcp_f32_e32 v75, v75
	v_rcp_f32_e32 v76, v76
	v_rcp_f32_e32 v77, v77
	v_rcp_f32_e32 v70, v70
	v_rcp_f32_e32 v71, v71
	v_rcp_f32_e32 v72, v72
	v_rcp_f32_e32 v73, v73
	v_rcp_f32_e32 v66, v66
	v_rcp_f32_e32 v67, v67
	v_rcp_f32_e32 v68, v68
	v_rcp_f32_e32 v69, v69
	v_mul_f32_e32 v2, v2, v78
	v_mul_f32_e32 v3, v3, v79
	v_mul_f32_e32 v50, v50, v78
	v_mul_f32_e32 v51, v51, v79
	v_mul_f32_e32 v34, v34, v78
	v_mul_f32_e32 v35, v35, v79
	v_mul_f32_e32 v18, v18, v78
	v_mul_f32_e32 v19, v19, v79
	v_cvt_pk_bf16_f32 v2, v2, v3
	v_cvt_pk_bf16_f32 v50, v50, v51
	v_cvt_pk_bf16_f32 v34, v34, v35
	v_cvt_pk_bf16_f32 v18, v18, v19
	v_mov_b32_dpp v3, v2 quad_perm:[1,0,3,2] row_mask:0xf bank_mask:0xf
	v_mov_b32_dpp v51, v50 quad_perm:[1,0,3,2] row_mask:0xf bank_mask:0xf
	v_mov_b32_dpp v35, v34 quad_perm:[1,0,3,2] row_mask:0xf bank_mask:0xf
	v_mov_b32_dpp v19, v18 quad_perm:[1,0,3,2] row_mask:0xf bank_mask:0xf
	v_perm_b32 v2, v3, v2, v84
	v_perm_b32 v50, v51, v50, v84
	v_perm_b32 v34, v35, v34, v84
	v_perm_b32 v18, v19, v18, v84
	global_store_dword v82, v2, s[6:7]
	global_store_dword v82, v50, s[6:7] offset:64
	global_store_dword v82, v34, s[6:7] offset:128
	global_store_dword v82, v18, s[6:7] offset:192
	v_mul_f32_e32 v4, v4, v80
	v_mul_f32_e32 v5, v5, v81
	v_mul_f32_e32 v52, v52, v80
	v_mul_f32_e32 v53, v53, v81
	v_mul_f32_e32 v36, v36, v80
	v_mul_f32_e32 v37, v37, v81
	v_mul_f32_e32 v20, v20, v80
	v_mul_f32_e32 v21, v21, v81
	v_add_u32_e32 v82, 0x1000, v82
	v_cvt_pk_bf16_f32 v4, v4, v5
	v_cvt_pk_bf16_f32 v52, v52, v53
	v_cvt_pk_bf16_f32 v36, v36, v37
	v_cvt_pk_bf16_f32 v20, v20, v21
	v_mov_b32_dpp v5, v4 quad_perm:[1,0,3,2] row_mask:0xf bank_mask:0xf
	v_mov_b32_dpp v53, v52 quad_perm:[1,0,3,2] row_mask:0xf bank_mask:0xf
	v_mov_b32_dpp v37, v36 quad_perm:[1,0,3,2] row_mask:0xf bank_mask:0xf
	v_mov_b32_dpp v21, v20 quad_perm:[1,0,3,2] row_mask:0xf bank_mask:0xf
	v_perm_b32 v4, v5, v4, v84
	v_perm_b32 v52, v53, v52, v84
	v_perm_b32 v36, v37, v36, v84
	v_perm_b32 v20, v21, v20, v84
	global_store_dword v82, v4, s[6:7]
	global_store_dword v82, v52, s[6:7] offset:64
	global_store_dword v82, v36, s[6:7] offset:128
	global_store_dword v82, v20, s[6:7] offset:192
	v_mul_f32_e32 v6, v6, v74
	v_mul_f32_e32 v7, v7, v75
	v_mul_f32_e32 v54, v54, v74
	v_mul_f32_e32 v55, v55, v75
	v_mul_f32_e32 v38, v38, v74
	v_mul_f32_e32 v39, v39, v75
	v_mul_f32_e32 v22, v22, v74
	v_mul_f32_e32 v23, v23, v75
; __device__ __forceinline__ int crow(int r, int hi) { return (r & 3) + 8 * (r >> 2) + 4 * hi; }
; __device__ __forceinline__ unsigned cvtpk(float lo, float hi) { return pg8::cvt_pk_bf16(lo, hi); }
; __device__ __forceinline__ void attn_block(const BlockRef& cur, const BlockRef& nxt, char* lds, Seam& S) {
;     ...
;     bf16* Ow = cur.O + (size_t)(wid * QBLK) * LD;
; #pragma unroll
;     for (int r = 0; r < 16; ++r) { const int orow = crow(r, hi);
; #pragma unroll
;         for (int d0 = 0; d0 < 4; ++d0) { const float v = o[d0][r] * rli[r];
;             const float vn = __shfl_xor(v, 1);
;             if ((r32 & 1) == 0) *(unsigned*)(Ow + (size_t)orow * LD + d0 * 32 + r32) = cvtpk(v, vn); } }
	v_add_u32_e32 v82, 0x3000, v82
	v_cvt_pk_bf16_f32 v6, v6, v7
	v_cvt_pk_bf16_f32 v54, v54, v55
	v_cvt_pk_bf16_f32 v38, v38, v39
	v_cvt_pk_bf16_f32 v22, v22, v23
	v_mov_b32_dpp v7, v6 quad_perm:[1,0,3,2] row_mask:0xf bank_mask:0xf
	v_mov_b32_dpp v55, v54 quad_perm:[1,0,3,2] row_mask:0xf bank_mask:0xf
	v_mov_b32_dpp v39, v38 quad_perm:[1,0,3,2] row_mask:0xf bank_mask:0xf
	v_mov_b32_dpp v23, v22 quad_perm:[1,0,3,2] row_mask:0xf bank_mask:0xf
	v_perm_b32 v6, v7, v6, v84
	v_perm_b32 v54, v55, v54, v84
	v_perm_b32 v38, v39, v38, v84
	v_perm_b32 v22, v23, v22, v84
	global_store_dword v82, v6, s[6:7]
	global_store_dword v82, v54, s[6:7] offset:64
	global_store_dword v82, v38, s[6:7] offset:128
	global_store_dword v82, v22, s[6:7] offset:192
	v_mul_f32_e32 v8, v8, v76
	v_mul_f32_e32 v9, v9, v77
	v_mul_f32_e32 v56, v56, v76
	v_mul_f32_e32 v57, v57, v77
	v_mul_f32_e32 v40, v40, v76
	v_mul_f32_e32 v41, v41, v77
	v_mul_f32_e32 v24, v24, v76
	v_mul_f32_e32 v25, v25, v77
	v_add_u32_e32 v82, 0x1000, v82
	v_cvt_pk_bf16_f32 v8, v8, v9
	v_cvt_pk_bf16_f32 v56, v56, v57
	v_cvt_pk_bf16_f32 v40, v40, v41
	v_cvt_pk_bf16_f32 v24, v24, v25
	v_mov_b32_dpp v9, v8 quad_perm:[1,0,3,2] row_mask:0xf bank_mask:0xf
	v_mov_b32_dpp v57, v56 quad_perm:[1,0,3,2] row_mask:0xf bank_mask:0xf
	v_mov_b32_dpp v41, v40 quad_perm:[1,0,3,2] row_mask:0xf bank_mask:0xf
	v_mov_b32_dpp v25, v24 quad_perm:[1,0,3,2] row_mask:0xf bank_mask:0xf
	v_perm_b32 v8, v9, v8, v84
	v_perm_b32 v56, v57, v56, v84
	v_perm_b32 v40, v41, v40, v84
	v_perm_b32 v24, v25, v24, v84
	global_store_dword v82, v8, s[6:7]
	global_store_dword v82, v56, s[6:7] offset:64
	global_store_dword v82, v40, s[6:7] offset:128
	global_store_dword v82, v24, s[6:7] offset:192
	v_mul_f32_e32 v10, v10, v70
	v_mul_f32_e32 v11, v11, v71
	v_mul_f32_e32 v58, v58, v70
	v_mul_f32_e32 v59, v59, v71
	v_mul_f32_e32 v42, v42, v70
	v_mul_f32_e32 v43, v43, v71
	v_mul_f32_e32 v26, v26, v70
	v_mul_f32_e32 v27, v27, v71
	v_add_u32_e32 v82, 0x3000, v82
	v_cvt_pk_bf16_f32 v10, v10, v11
	v_cvt_pk_bf16_f32 v58, v58, v59
	v_cvt_pk_bf16_f32 v42, v42, v43
	v_cvt_pk_bf16_f32 v26, v26, v27
	v_mov_b32_dpp v11, v10 quad_perm:[1,0,3,2] row_mask:0xf bank_mask:0xf
	v_mov_b32_dpp v59, v58 quad_perm:[1,0,3,2] row_mask:0xf bank_mask:0xf
	v_mov_b32_dpp v43, v42 quad_perm:[1,0,3,2] row_mask:0xf bank_mask:0xf
	v_mov_b32_dpp v27, v26 quad_perm:[1,0,3,2] row_mask:0xf bank_mask:0xf
	v_perm_b32 v10, v11, v10, v84
	v_perm_b32 v58, v59, v58, v84
	v_perm_b32 v42, v43, v42, v84
	v_perm_b32 v26, v27, v26, v84
	global_store_dword v82, v10, s[6:7]
	global_store_dword v82, v58, s[6:7] offset:64
	global_store_dword v82, v42, s[6:7] offset:128
	global_store_dword v82, v26, s[6:7] offset:192
	v_mul_f32_e32 v12, v12, v72
	v_mul_f32_e32 v13, v13, v73
	v_mul_f32_e32 v60, v60, v72
	v_mul_f32_e32 v61, v61, v73
	v_mul_f32_e32 v44, v44, v72
	v_mul_f32_e32 v45, v45, v73
	v_mul_f32_e32 v28, v28, v72
	v_mul_f32_e32 v29, v29, v73
	v_add_u32_e32 v82, 0x1000, v82
	v_cvt_pk_bf16_f32 v12, v12, v13
	v_cvt_pk_bf16_f32 v60, v60, v61
	v_cvt_pk_bf16_f32 v44, v44, v45
	v_cvt_pk_bf16_f32 v28, v28, v29
	v_mov_b32_dpp v13, v12 quad_perm:[1,0,3,2] row_mask:0xf bank_mask:0xf
	v_mov_b32_dpp v61, v60 quad_perm:[1,0,3,2] row_mask:0xf bank_mask:0xf
	v_mov_b32_dpp v45, v44 quad_perm:[1,0,3,2] row_mask:0xf bank_mask:0xf
	v_mov_b32_dpp v29, v28 quad_perm:[1,0,3,2] row_mask:0xf bank_mask:0xf
	v_perm_b32 v12, v13, v12, v84
	v_perm_b32 v60, v61, v60, v84
	v_perm_b32 v44, v45, v44, v84
	v_perm_b32 v28, v29, v28, v84
	global_store_dword v82, v12, s[6:7]
	global_store_dword v82, v60, s[6:7] offset:64
	global_store_dword v82, v44, s[6:7] offset:128
	global_store_dword v82, v28, s[6:7] offset:192
	v_mul_f32_e32 v14, v14, v66
	v_mul_f32_e32 v15, v15, v67
	v_mul_f32_e32 v62, v62, v66
	v_mul_f32_e32 v63, v63, v67
	v_mul_f32_e32 v46, v46, v66
	v_mul_f32_e32 v47, v47, v67
	v_mul_f32_e32 v30, v30, v66
	v_mul_f32_e32 v31, v31, v67
	v_add_u32_e32 v82, 0x3000, v82
	v_cvt_pk_bf16_f32 v14, v14, v15
	v_cvt_pk_bf16_f32 v62, v62, v63
	v_cvt_pk_bf16_f32 v46, v46, v47
	v_cvt_pk_bf16_f32 v30, v30, v31
	v_mov_b32_dpp v15, v14 quad_perm:[1,0,3,2] row_mask:0xf bank_mask:0xf
	v_mov_b32_dpp v63, v62 quad_perm:[1,0,3,2] row_mask:0xf bank_mask:0xf
	v_mov_b32_dpp v47, v46 quad_perm:[1,0,3,2] row_mask:0xf bank_mask:0xf
	v_mov_b32_dpp v31, v30 quad_perm:[1,0,3,2] row_mask:0xf bank_mask:0xf
	v_perm_b32 v14, v15, v14, v84
	v_perm_b32 v62, v63, v62, v84
	v_perm_b32 v46, v47, v46, v84
	v_perm_b32 v30, v31, v30, v84
	global_store_dword v82, v14, s[6:7]
	global_store_dword v82, v62, s[6:7] offset:64
	global_store_dword v82, v46, s[6:7] offset:128
	global_store_dword v82, v30, s[6:7] offset:192
	v_mul_f32_e32 v16, v16, v68
	v_mul_f32_e32 v17, v17, v69
	v_mul_f32_e32 v64, v64, v68
	v_mul_f32_e32 v65, v65, v69
	v_mul_f32_e32 v48, v48, v68
	v_mul_f32_e32 v49, v49, v69
	v_mul_f32_e32 v32, v32, v68
	v_mul_f32_e32 v33, v33, v69
	v_add_u32_e32 v82, 0x1000, v82
	v_cvt_pk_bf16_f32 v16, v16, v17
	v_cvt_pk_bf16_f32 v64, v64, v65
	v_cvt_pk_bf16_f32 v48, v48, v49
	v_cvt_pk_bf16_f32 v32, v32, v33
	v_mov_b32_dpp v17, v16 quad_perm:[1,0,3,2] row_mask:0xf bank_mask:0xf
	v_mov_b32_dpp v65, v64 quad_perm:[1,0,3,2] row_mask:0xf bank_mask:0xf
	v_mov_b32_dpp v49, v48 quad_perm:[1,0,3,2] row_mask:0xf bank_mask:0xf
	v_mov_b32_dpp v33, v32 quad_perm:[1,0,3,2] row_mask:0xf bank_mask:0xf
	v_perm_b32 v16, v17, v16, v84
	v_perm_b32 v64, v65, v64, v84
	v_perm_b32 v48, v49, v48, v84
	v_perm_b32 v32, v33, v32, v84
	global_store_dword v82, v16, s[6:7]
	global_store_dword v82, v64, s[6:7] offset:64
	global_store_dword v82, v48, s[6:7] offset:128
	global_store_dword v82, v32, s[6:7] offset:192
	s_branch .LBB0_1292
